# sp3: second workgroup of each CU runs its retention scan unit after its MLA tiles (overlaps the other workgroup's MLA)
# baseline (speedup 1.0000x reference)
.LBB0_431:
	s_and_b64 vcc, exec, s[0:1]
	s_cbranch_vccz .LBB0_542
	v_readlane_b32 s0, v246, 23
	v_readlane_b32 s1, v246, 24
	v_readlane_b32 s56, v244, 40
	s_andn2_b64 vcc, exec, s[0:1]
	v_readlane_b32 s0, v246, 0
	v_readlane_b32 s70, v244, 54
	v_readlane_b32 s71, v244, 55
	v_readlane_b32 s57, v244, 41
	v_readlane_b32 s58, v244, 42
	v_readlane_b32 s59, v244, 43
	v_readlane_b32 s60, v244, 44
	v_readlane_b32 s61, v244, 45
	v_readlane_b32 s62, v244, 46
	v_readlane_b32 s63, v244, 47
	v_readlane_b32 s64, v244, 48
	v_readlane_b32 s65, v244, 49
	v_readlane_b32 s66, v244, 50
	v_readlane_b32 s67, v244, 51
	v_readlane_b32 s68, v244, 52
	v_readlane_b32 s69, v244, 53
	s_cbranch_vccnz .LBB0_436
	s_mov_b32 s8, 0
	s_cmp_ge_u32 s0, 0x100
	s_cbranch_scc1 .LBB0_436

.LBB0_434:
	s_cmp_gt_u32 s1, 1
	s_cselect_b32 s3, 0x43, 1
	s_add_i32 s3, s3, s2
	s_sub_i32 s3, s3, 57
	s_cmp_eq_u32 s1, 0
	v_mov_b32_e32 v0, s3
	s_cselect_b32 s3, 1, 0x43
	s_add_i32 s3, s3, s2
	v_mov_b32_e32 v4, s1
	s_sub_i32 s3, s3, 58
	s_add_i32 s4, s1, 1
	v_cndmask_b32_e32 v4, v0, v4, vcc
	v_mov_b32_e32 v0, s3
	v_mov_b32_e32 v6, s4
	s_add_i32 s3, s2, 8
	s_add_i32 s4, s1, 2
	v_cndmask_b32_e32 v6, v0, v6, vcc
	v_mov_b32_e32 v0, s3
	v_mov_b32_e32 v8, s4
	v_cndmask_b32_e32 v0, v0, v8, vcc
	s_add_i32 s3, s2, 7
	s_add_i32 s4, s1, 3
	v_lshlrev_b64 v[8:9], 15, v[0:1]
	v_mov_b32_e32 v0, s3
	v_mov_b32_e32 v10, s4
	v_cndmask_b32_e32 v0, v0, v10, vcc
	s_add_i32 s3, s2, 6
	s_add_i32 s4, s1, 4
	v_lshlrev_b64 v[10:11], 15, v[0:1]
	v_mov_b32_e32 v0, s3
	v_mov_b32_e32 v12, s4
	v_cndmask_b32_e32 v0, v0, v12, vcc
	s_add_i32 s3, s2, 5
	s_add_i32 s4, s1, 5
	v_lshlrev_b64 v[12:13], 15, v[0:1]
	v_mov_b32_e32 v0, s3
	v_mov_b32_e32 v14, s4
	v_ashrrev_i32_e32 v5, 31, v4
	v_cndmask_b32_e32 v0, v0, v14, vcc
	s_add_i32 s3, s2, 4
	s_add_i32 s4, s1, 6
	v_lshlrev_b64 v[4:5], 15, v[4:5]
	v_ashrrev_i32_e32 v7, 31, v6
	v_lshlrev_b64 v[14:15], 15, v[0:1]
	v_mov_b32_e32 v0, s3
	v_mov_b32_e32 v16, s4
	v_lshl_add_u64 v[4:5], v[2:3], 0, v[4:5]
	v_lshlrev_b64 v[6:7], 15, v[6:7]
	v_cndmask_b32_e32 v0, v0, v16, vcc
	s_add_i32 s3, s2, 3
	s_add_i32 s4, s1, 7
	global_load_dword v26, v[4:5], off
	v_lshl_add_u64 v[6:7], v[2:3], 0, v[6:7]
	v_lshlrev_b64 v[16:17], 15, v[0:1]
	v_mov_b32_e32 v0, s3
	v_mov_b32_e32 v18, s4
	global_load_dword v27, v[6:7], off
	v_lshl_add_u64 v[8:9], v[2:3], 0, v[8:9]
	v_cndmask_b32_e32 v0, v0, v18, vcc
	s_add_i32 s3, s2, 2
	s_add_i32 s4, s1, 8
	global_load_dword v28, v[8:9], off
	v_lshl_add_u64 v[10:11], v[2:3], 0, v[10:11]
	v_lshlrev_b64 v[18:19], 15, v[0:1]
	v_mov_b32_e32 v0, s3
	v_mov_b32_e32 v20, s4
	global_load_dword v29, v[10:11], off
	v_lshl_add_u64 v[12:13], v[2:3], 0, v[12:13]
	v_cndmask_b32_e32 v0, v0, v20, vcc
	s_add_i32 s3, s2, 1
	s_add_i32 s4, s1, 9
	global_load_dword v30, v[12:13], off
	v_lshl_add_u64 v[14:15], v[2:3], 0, v[14:15]
	v_lshlrev_b64 v[20:21], 15, v[0:1]
	v_mov_b32_e32 v0, s3
	v_mov_b32_e32 v22, s4
	global_load_dword v31, v[14:15], off
	v_lshl_add_u64 v[16:17], v[2:3], 0, v[16:17]
	v_cndmask_b32_e32 v0, v0, v22, vcc
	s_add_i32 s3, s1, 10
	global_load_dword v32, v[16:17], off
	v_lshl_add_u64 v[18:19], v[2:3], 0, v[18:19]
	v_lshlrev_b64 v[22:23], 15, v[0:1]
	v_mov_b32_e32 v0, s2
	v_mov_b32_e32 v36, s3
	global_load_dword v33, v[18:19], off
	v_lshl_add_u64 v[20:21], v[2:3], 0, v[20:21]
	v_cndmask_b32_e32 v0, v0, v36, vcc
	global_load_dword v34, v[20:21], off
	v_lshl_add_u64 v[22:23], v[2:3], 0, v[22:23]
	v_lshlrev_b64 v[36:37], 15, v[0:1]
	global_load_dword v35, v[22:23], off
	v_lshl_add_u64 v[36:37], v[2:3], 0, v[36:37]
	global_load_dword v0, v[36:37], off
	s_add_i32 s2, s2, -11
	s_add_i32 s3, s1, 11
	global_store_dword v[4:5], v24, off
	s_cmp_lt_u32 s1, 55
	s_mov_b32 s1, s3
	s_waitcnt vmcnt(0)
	v_fmac_f32_e32 v26, v25, v24
	global_store_dword v[6:7], v26, off
	v_fmac_f32_e32 v27, v25, v26
	global_store_dword v[8:9], v27, off
	v_fmac_f32_e32 v28, v25, v27
	global_store_dword v[10:11], v28, off
	v_fmac_f32_e32 v29, v25, v28
	global_store_dword v[12:13], v29, off
	v_fmac_f32_e32 v30, v25, v29
	global_store_dword v[14:15], v30, off
	v_fmac_f32_e32 v31, v25, v30
	global_store_dword v[16:17], v31, off
	v_fmac_f32_e32 v32, v25, v31
	global_store_dword v[18:19], v32, off
	v_fmac_f32_e32 v33, v25, v32
	global_store_dword v[20:21], v33, off
	v_fmac_f32_e32 v34, v25, v33
	global_store_dword v[22:23], v34, off
	v_fmac_f32_e32 v35, v25, v34
	global_store_dword v[36:37], v35, off
	v_fmac_f32_e32 v0, v25, v35
	v_mov_b32_e32 v24, v0
	s_cbranch_scc1 .LBB0_434
	s_add_i32 s0, s0, s10
	s_cmpk_lt_i32 s0, 0x200
	s_cbranch_scc1 .LBB0_433
	s_cmp_eq_u32 s8, 1
	s_cbranch_scc1 .LBB0_542

.Lsp3_late:
	v_readlane_b32 s0, v246, 0
	s_cmp_lt_u32 s0, 0x100
	s_cbranch_scc1 .LBB0_542
	v_readlane_b32 s70, v244, 54
	v_readlane_b32 s71, v244, 55
	s_mov_b32 s8, 1
	s_branch .LBB0_433
